# attention: one static s_setprio 1 for waves 4-7 over the attention phase, per-cluster setprio flips deleted
# baseline (speedup 1.0000x reference)
.LBB0_793:
	v_writelane_b32 v242, s20, 21
	v_writelane_b32 v242, s21, 22
	v_writelane_b32 v242, s22, 23
	v_writelane_b32 v242, s23, 24
	v_writelane_b32 v242, s24, 25
	v_writelane_b32 v242, s25, 26
	s_cmp_ge_i32 s45, s72
	s_cbranch_scc1 .LBB0_828
	v_readfirstlane_b32 s20, v160
	s_nop 3
	s_cmpk_lt_u32 s20, 0x100
	s_cbranch_scc1 .Latt_noprio
	s_setprio 1
.Latt_noprio:
	v_readlane_b32 s4, v247, 2
	s_lshl_b32 s26, s56, 3
	v_readlane_b32 s5, v247, 3
	v_readlane_b32 s8, v247, 6
	v_readlane_b32 s9, v247, 7
	s_lshl_b64 s[2:3], s[26:27], 2
	s_mov_b64 s[4:5], s[8:9]
	v_readlane_b32 s6, v247, 4
	s_add_u32 s4, s4, s2
	s_addc_u32 s5, s5, s3
	s_mov_b32 s6, s45
	v_readlane_b32 s7, v247, 5
	v_readlane_b32 s10, v247, 8
	v_readlane_b32 s11, v247, 9
	v_readlane_b32 s12, v247, 10
	v_readlane_b32 s13, v247, 11
	v_readlane_b32 s14, v247, 12
	v_readlane_b32 s15, v247, 13
	v_readlane_b32 s16, v247, 14
	v_readlane_b32 s17, v247, 15
	v_readlane_b32 s18, v247, 16
	v_readlane_b32 s19, v247, 17
	s_branch .LBB0_796

.Latt_noskip:
	ds_read_b128 v[64:67], v189
	ds_read_b128 v[164:167], v189 offset:32
	ds_read_b128 v[168:171], v189 offset:64
	ds_read_b128 v[172:175], v189 offset:96
	s_waitcnt lgkmcnt(3)
	v_mfma_f32_32x32x16_bf16 v[80:95], v[64:67], v[96:99], v[206:221]
	v_mfma_f32_32x32x16_bf16 v[64:79], v[64:67], v[112:115], v[222:237]
	s_waitcnt lgkmcnt(2)
	v_mfma_f32_32x32x16_bf16 v[80:95], v[164:167], v[100:103], v[80:95]
	v_mfma_f32_32x32x16_bf16 v[64:79], v[164:167], v[116:119], v[64:79]
	s_waitcnt lgkmcnt(1)
	v_mfma_f32_32x32x16_bf16 v[80:95], v[168:171], v[104:107], v[80:95]
	v_mfma_f32_32x32x16_bf16 v[64:79], v[168:171], v[120:123], v[64:79]
	s_waitcnt lgkmcnt(0)
	v_mfma_f32_32x32x16_bf16 v[80:95], v[172:175], v[108:111], v[80:95]
	v_mfma_f32_32x32x16_bf16 v[64:79], v[172:175], v[124:127], v[64:79]
	s_cmp_lt_i32 s9, 2
	s_cbranch_scc1 .LBB0_818
	s_cmp_eq_u32 s9, 2
	s_cselect_b64 s[50:51], -1, 0
	s_cbranch_execz .LBB0_819
	s_branch .LBB0_820

.Latt_pv:
	s_waitcnt lgkmcnt(3)
	v_mfma_f32_32x32x16_bf16 v[32:47], v[164:167], v[80:83], v[32:47]
	v_mfma_f32_32x32x16_bf16 v[16:31], v[164:167], v[64:67], v[16:31]
	s_waitcnt lgkmcnt(2)
	v_mfma_f32_32x32x16_bf16 v[48:63], v[168:171], v[80:83], v[48:63]
	v_mfma_f32_32x32x16_bf16 v[0:15], v[168:171], v[64:67], v[0:15]
	s_waitcnt lgkmcnt(1)
	v_mfma_f32_32x32x16_bf16 v[32:47], v[172:175], v[84:87], v[32:47]
	v_mfma_f32_32x32x16_bf16 v[16:31], v[172:175], v[68:71], v[16:31]
	s_waitcnt lgkmcnt(0)
	v_mfma_f32_32x32x16_bf16 v[48:63], v[238:241], v[84:87], v[48:63]
	v_mfma_f32_32x32x16_bf16 v[0:15], v[238:241], v[68:71], v[0:15]
	s_branch .Latt_tail

.LBB0_828:
	s_setprio 0
	v_readlane_b32 s20, v242, 21
	v_readlane_b32 s21, v242, 22
	v_readlane_b32 s22, v242, 23
	v_readlane_b32 s23, v242, 24
	v_readlane_b32 s24, v242, 25
	v_readlane_b32 s25, v242, 26
	s_waitcnt vmcnt(0)
	s_waitcnt vmcnt(0) lgkmcnt(0)
	s_barrier
	s_mov_b64 s[2:3], exec
	v_readlane_b32 s4, v247, 0
	v_readlane_b32 s5, v247, 1
	v_readlane_b32 s6, v242, 3
	s_and_b64 s[4:5], s[2:3], s[4:5]
	v_readlane_b32 s7, v242, 4
	s_mov_b64 exec, s[4:5]
	s_cbranch_execz .LBB0_880
	v_readlane_b32 s4, v243, 47
	s_waitcnt vmcnt(0) expcnt(0) lgkmcnt(0)
	s_nop 0
	v_mov_b32_e32 v0, s4
	ds_read_b32 v2, v0
	v_readlane_b32 s4, v243, 48
	s_waitcnt lgkmcnt(0)
	v_cmp_ne_u32_e32 vcc, 0, v2
	v_mov_b32_e32 v0, s4
	ds_read_b32 v0, v0
	s_cbranch_vccnz .LBB0_844
	s_mov_b32 s4, 1
	s_branch .LBB0_832
